# dn_prep 32-row forward substitution rewritten with packed f32 FMAs on chain pairs (same chains, same order), L rows prefetched 2-3 rows ahead
# baseline (speedup 1.0000x reference)
; DI void dn_prep_item(const Params& p, int l, int item, int next_item, u32x4 (&pre)[12], unsigned char* lds, int tid) {
;     ...
;             f32x4 cur[8], nxt[8];
;             cur[0] = *(const f32x4*)(Lb + 64);
; #pragma unroll
;             for (int i = 1; i < 32; ++i) {
;                 if (i < 31) {
; #pragma unroll
;                     for (int q = 0; q < 8; ++q) if (4 * q < i + 1) nxt[q] = *(const f32x4*)(Lb + (i + 1) * 64 + 4 * q);
;                 }
;                 float a0 = x[i], a1 = 0.f, a2 = 0.f, a3 = 0.f;
; #pragma unroll
;                 for (int j = 0; j < i; ++j) { const float lv = cur[j >> 2][j & 3];
;                     if ((j & 3) == 0) a0 -= lv * x[j]; else if ((j & 3) == 1) a1 -= lv * x[j]; else if ((j & 3) == 2) a2 -= lv * x[j]; else a3 -= lv * x[j]; }
;                 x[i] = (a0 + a1) + (a2 + a3);
; #pragma unroll
;                 for (int q = 0; q < 8; ++q) cur[q] = nxt[q];
;             }
.LBB0_496:
	s_or_b64 exec, exec, s[6:7]
	s_waitcnt lgkmcnt(0)
	v_mov_b32_e32 v46, 0
	v_mov_b32_e32 v47, 0
	ds_read_b128 v[78:81], v35 offset:50176
	ds_read_b128 v[82:85], v35 offset:50432
	ds_read_b128 v[86:89], v35 offset:50688
	ds_read_b128 v[90:93], v35 offset:50944
	s_waitcnt lgkmcnt(3)
	v_fma_f32 v1, -v78, v0, v1
	v_add_f32_e32 v1, 0, v1
	s_waitcnt lgkmcnt(2)
	v_fma_f32 v38, -v82, v0, v2
	v_fma_f32 v39, -v83, v1, 0
	ds_read_b128 v[94:97], v35 offset:51200
	ds_read_b128 v[98:101], v35 offset:51216
	v_add_f32_e32 v2, v38, v39
	s_waitcnt lgkmcnt(3)
	v_fma_f32 v42, -v86, v0, v3
	v_fma_f32 v43, -v87, v1, 0
	v_fma_f32 v44, -v88, v2, 0
	ds_read_b128 v[102:105], v35 offset:51456
	ds_read_b128 v[106:109], v35 offset:51472
	v_add_f32_e32 v42, v42, v43
	v_add_f32_e32 v3, v42, v44
	s_waitcnt lgkmcnt(4)
	v_fma_f32 v38, -v90, v0, v4
	v_fma_f32 v39, -v91, v1, 0
	v_pk_fma_f32 v[40:41], v[92:93], v[2:3], v[46:47] neg_lo:[1,0,0] neg_hi:[1,0,0]
	ds_read_b128 v[110:113], v35 offset:51712
	ds_read_b128 v[114:117], v35 offset:51728
	v_add_f32_e32 v38, v39, v38
	v_add_f32_e32 v40, v40, v41
	v_add_f32_e32 v4, v38, v40
	s_waitcnt lgkmcnt(4)
	v_fma_f32 v42, -v94, v0, v5
	v_fma_f32 v43, -v95, v1, 0
	v_pk_fma_f32 v[44:45], v[96:97], v[2:3], v[46:47] neg_lo:[1,0,0] neg_hi:[1,0,0]
	ds_read_b128 v[118:121], v35 offset:51968
	ds_read_b128 v[122:125], v35 offset:51984
	v_pk_fma_f32 v[42:43], v[98:99], v[4:5], v[42:43] neg_lo:[1,0,0] neg_hi:[1,0,0]
	s_waitcnt lgkmcnt(4)
	v_fma_f32 v38, -v102, v0, v6
	v_add_f32_e32 v42, v43, v42
	v_fma_f32 v39, -v103, v1, 0
	v_add_f32_e32 v44, v44, v45
	v_pk_fma_f32 v[40:41], v[104:105], v[2:3], v[46:47] neg_lo:[1,0,0] neg_hi:[1,0,0]
	v_add_f32_e32 v5, v42, v44
	ds_read_b128 v[212:215], v35 offset:52224
	ds_read_b128 v[216:219], v35 offset:52240
	ds_read_b128 v[220:223], v35 offset:52256
	v_pk_fma_f32 v[38:39], v[106:107], v[4:5], v[38:39] neg_lo:[1,0,0] neg_hi:[1,0,0]
	s_waitcnt lgkmcnt(5)
	v_fma_f32 v42, -v110, v0, v7
	v_add_f32_e32 v38, v39, v38
	v_fma_f32 v43, -v111, v1, 0
	v_add_f32_e32 v40, v40, v41
	v_pk_fma_f32 v[44:45], v[112:113], v[2:3], v[46:47] neg_lo:[1,0,0] neg_hi:[1,0,0]
	v_add_f32_e32 v6, v38, v40
	ds_read_b128 v[224:227], v35 offset:52480
	ds_read_b128 v[228:231], v35 offset:52496
	ds_read_b128 v[232:235], v35 offset:52512
	v_pk_fma_f32 v[42:43], v[114:115], v[4:5], v[42:43] neg_lo:[1,0,0] neg_hi:[1,0,0]
	v_pk_fma_f32 v[44:45], v[116:117], v[6:7], v[44:45] neg_lo:[1,0,0] neg_hi:[1,0,0]
	s_waitcnt lgkmcnt(6)
	v_fma_f32 v38, -v118, v0, v8
	v_add_f32_e32 v42, v43, v42
	v_fma_f32 v39, -v119, v1, 0
	v_add_f32_e32 v44, v44, v45
	v_pk_fma_f32 v[40:41], v[120:121], v[2:3], v[46:47] neg_lo:[1,0,0] neg_hi:[1,0,0]
	v_add_f32_e32 v7, v42, v44
	ds_read_b128 v[236:239], v35 offset:52736
	ds_read_b128 v[240:243], v35 offset:52752
	ds_read_b128 v[62:65], v35 offset:52768
	v_pk_fma_f32 v[38:39], v[122:123], v[4:5], v[38:39] neg_lo:[1,0,0] neg_hi:[1,0,0]
	v_pk_fma_f32 v[40:41], v[124:125], v[6:7], v[40:41] neg_lo:[1,0,0] neg_hi:[1,0,0]
	s_waitcnt lgkmcnt(6)
	v_fma_f32 v42, -v212, v0, v9
	v_add_f32_e32 v38, v39, v38
	v_fma_f32 v43, -v213, v1, 0
	v_add_f32_e32 v40, v40, v41
	v_pk_fma_f32 v[44:45], v[214:215], v[2:3], v[46:47] neg_lo:[1,0,0] neg_hi:[1,0,0]
	v_add_f32_e32 v8, v38, v40
	ds_read_b128 v[78:81], v35 offset:52992
	ds_read_b128 v[82:85], v35 offset:53008
	ds_read_b128 v[86:89], v35 offset:53024
	v_pk_fma_f32 v[42:43], v[216:217], v[4:5], v[42:43] neg_lo:[1,0,0] neg_hi:[1,0,0]
	v_pk_fma_f32 v[44:45], v[218:219], v[6:7], v[44:45] neg_lo:[1,0,0] neg_hi:[1,0,0]
	v_pk_fma_f32 v[42:43], v[220:221], v[8:9], v[42:43] neg_lo:[1,0,0] neg_hi:[1,0,0]
	s_waitcnt lgkmcnt(6)
	v_fma_f32 v38, -v224, v0, v10
	v_add_f32_e32 v42, v43, v42
	v_fma_f32 v39, -v225, v1, 0
	v_add_f32_e32 v44, v44, v45
	v_pk_fma_f32 v[40:41], v[226:227], v[2:3], v[46:47] neg_lo:[1,0,0] neg_hi:[1,0,0]
	v_add_f32_e32 v9, v42, v44
	ds_read_b128 v[90:93], v35 offset:53248
	ds_read_b128 v[94:97], v35 offset:53264
	ds_read_b128 v[98:101], v35 offset:53280
	ds_read_b128 v[102:105], v35 offset:53296
	v_pk_fma_f32 v[38:39], v[228:229], v[4:5], v[38:39] neg_lo:[1,0,0] neg_hi:[1,0,0]
	v_pk_fma_f32 v[40:41], v[230:231], v[6:7], v[40:41] neg_lo:[1,0,0] neg_hi:[1,0,0]
	v_pk_fma_f32 v[38:39], v[232:233], v[8:9], v[38:39] neg_lo:[1,0,0] neg_hi:[1,0,0]
	s_waitcnt lgkmcnt(7)
	v_fma_f32 v42, -v236, v0, v11
	v_add_f32_e32 v38, v39, v38
	v_fma_f32 v43, -v237, v1, 0
	v_add_f32_e32 v40, v40, v41
	v_pk_fma_f32 v[44:45], v[238:239], v[2:3], v[46:47] neg_lo:[1,0,0] neg_hi:[1,0,0]
	v_add_f32_e32 v10, v38, v40
	ds_read_b128 v[106:109], v35 offset:53504
	ds_read_b128 v[110:113], v35 offset:53520
	ds_read_b128 v[114:117], v35 offset:53536
	ds_read_b128 v[118:121], v35 offset:53552
	v_pk_fma_f32 v[42:43], v[240:241], v[4:5], v[42:43] neg_lo:[1,0,0] neg_hi:[1,0,0]
	v_pk_fma_f32 v[44:45], v[242:243], v[6:7], v[44:45] neg_lo:[1,0,0] neg_hi:[1,0,0]
	v_pk_fma_f32 v[42:43], v[62:63], v[8:9], v[42:43] neg_lo:[1,0,0] neg_hi:[1,0,0]
	v_pk_fma_f32 v[44:45], v[64:65], v[10:11], v[44:45] neg_lo:[1,0,0] neg_hi:[1,0,0]
	s_waitcnt lgkmcnt(8)
	v_fma_f32 v38, -v78, v0, v12
	v_add_f32_e32 v42, v43, v42
	v_fma_f32 v39, -v79, v1, 0
	v_add_f32_e32 v44, v44, v45
	v_pk_fma_f32 v[40:41], v[80:81], v[2:3], v[46:47] neg_lo:[1,0,0] neg_hi:[1,0,0]
	v_add_f32_e32 v11, v42, v44
	ds_read_b128 v[122:125], v35 offset:53760
	ds_read_b128 v[212:215], v35 offset:53776
	ds_read_b128 v[216:219], v35 offset:53792
	ds_read_b128 v[220:223], v35 offset:53808
	v_pk_fma_f32 v[38:39], v[82:83], v[4:5], v[38:39] neg_lo:[1,0,0] neg_hi:[1,0,0]
	v_pk_fma_f32 v[40:41], v[84:85], v[6:7], v[40:41] neg_lo:[1,0,0] neg_hi:[1,0,0]
	v_pk_fma_f32 v[38:39], v[86:87], v[8:9], v[38:39] neg_lo:[1,0,0] neg_hi:[1,0,0]
	v_pk_fma_f32 v[40:41], v[88:89], v[10:11], v[40:41] neg_lo:[1,0,0] neg_hi:[1,0,0]
	s_waitcnt lgkmcnt(8)
; DI void dn_prep_item(const Params& p, int l, int item, int next_item, u32x4 (&pre)[12], unsigned char* lds, int tid) {
;     ...
;             f32x4 cur[8], nxt[8];
;             cur[0] = *(const f32x4*)(Lb + 64);
; #pragma unroll
;             for (int i = 1; i < 32; ++i) {
;                 if (i < 31) {
; #pragma unroll
;                     for (int q = 0; q < 8; ++q) if (4 * q < i + 1) nxt[q] = *(const f32x4*)(Lb + (i + 1) * 64 + 4 * q);
;                 }
;                 float a0 = x[i], a1 = 0.f, a2 = 0.f, a3 = 0.f;
; #pragma unroll
;                 for (int j = 0; j < i; ++j) { const float lv = cur[j >> 2][j & 3];
;                     if ((j & 3) == 0) a0 -= lv * x[j]; else if ((j & 3) == 1) a1 -= lv * x[j]; else if ((j & 3) == 2) a2 -= lv * x[j]; else a3 -= lv * x[j]; }
;                 x[i] = (a0 + a1) + (a2 + a3);
; #pragma unroll
;                 for (int q = 0; q < 8; ++q) cur[q] = nxt[q];
;             }
	v_fma_f32 v42, -v90, v0, v13
	v_add_f32_e32 v38, v39, v38
	v_fma_f32 v43, -v91, v1, 0
	v_add_f32_e32 v40, v40, v41
	v_pk_fma_f32 v[44:45], v[92:93], v[2:3], v[46:47] neg_lo:[1,0,0] neg_hi:[1,0,0]
	v_add_f32_e32 v12, v38, v40
	ds_read_b128 v[224:227], v35 offset:54016
	ds_read_b128 v[228:231], v35 offset:54032
	ds_read_b128 v[232:235], v35 offset:54048
	ds_read_b128 v[236:239], v35 offset:54064
	v_pk_fma_f32 v[42:43], v[94:95], v[4:5], v[42:43] neg_lo:[1,0,0] neg_hi:[1,0,0]
	v_pk_fma_f32 v[44:45], v[96:97], v[6:7], v[44:45] neg_lo:[1,0,0] neg_hi:[1,0,0]
	v_pk_fma_f32 v[42:43], v[98:99], v[8:9], v[42:43] neg_lo:[1,0,0] neg_hi:[1,0,0]
	v_pk_fma_f32 v[44:45], v[100:101], v[10:11], v[44:45] neg_lo:[1,0,0] neg_hi:[1,0,0]
	v_pk_fma_f32 v[42:43], v[102:103], v[12:13], v[42:43] neg_lo:[1,0,0] neg_hi:[1,0,0]
	s_waitcnt lgkmcnt(8)
	v_fma_f32 v38, -v106, v0, v14
	v_add_f32_e32 v42, v43, v42
	v_fma_f32 v39, -v107, v1, 0
	v_add_f32_e32 v44, v44, v45
	v_pk_fma_f32 v[40:41], v[108:109], v[2:3], v[46:47] neg_lo:[1,0,0] neg_hi:[1,0,0]
	v_add_f32_e32 v13, v42, v44
	v_pk_fma_f32 v[38:39], v[110:111], v[4:5], v[38:39] neg_lo:[1,0,0] neg_hi:[1,0,0]
	v_pk_fma_f32 v[40:41], v[112:113], v[6:7], v[40:41] neg_lo:[1,0,0] neg_hi:[1,0,0]
	v_pk_fma_f32 v[38:39], v[114:115], v[8:9], v[38:39] neg_lo:[1,0,0] neg_hi:[1,0,0]
	v_pk_fma_f32 v[40:41], v[116:117], v[10:11], v[40:41] neg_lo:[1,0,0] neg_hi:[1,0,0]
	v_pk_fma_f32 v[38:39], v[118:119], v[12:13], v[38:39] neg_lo:[1,0,0] neg_hi:[1,0,0]
	s_waitcnt lgkmcnt(4)
	v_fma_f32 v42, -v122, v0, v15
	v_add_f32_e32 v38, v39, v38
	v_fma_f32 v43, -v123, v1, 0
	v_add_f32_e32 v40, v40, v41
	v_pk_fma_f32 v[44:45], v[124:125], v[2:3], v[46:47] neg_lo:[1,0,0] neg_hi:[1,0,0]
	v_add_f32_e32 v14, v38, v40
	ds_read_b128 v[240:243], v35 offset:54272
	ds_read_b128 v[62:65], v35 offset:54288
	ds_read_b128 v[78:81], v35 offset:54304
	ds_read_b128 v[82:85], v35 offset:54320
	ds_read_b128 v[86:89], v35 offset:54336
	v_pk_fma_f32 v[42:43], v[212:213], v[4:5], v[42:43] neg_lo:[1,0,0] neg_hi:[1,0,0]
	v_pk_fma_f32 v[44:45], v[214:215], v[6:7], v[44:45] neg_lo:[1,0,0] neg_hi:[1,0,0]
	v_pk_fma_f32 v[42:43], v[216:217], v[8:9], v[42:43] neg_lo:[1,0,0] neg_hi:[1,0,0]
	v_pk_fma_f32 v[44:45], v[218:219], v[10:11], v[44:45] neg_lo:[1,0,0] neg_hi:[1,0,0]
	v_pk_fma_f32 v[42:43], v[220:221], v[12:13], v[42:43] neg_lo:[1,0,0] neg_hi:[1,0,0]
	v_pk_fma_f32 v[44:45], v[222:223], v[14:15], v[44:45] neg_lo:[1,0,0] neg_hi:[1,0,0]
	s_waitcnt lgkmcnt(5)
	v_fma_f32 v38, -v224, v0, v16
	v_add_f32_e32 v42, v43, v42
	v_fma_f32 v39, -v225, v1, 0
	v_add_f32_e32 v44, v44, v45
	v_pk_fma_f32 v[40:41], v[226:227], v[2:3], v[46:47] neg_lo:[1,0,0] neg_hi:[1,0,0]
	v_add_f32_e32 v15, v42, v44
	ds_read_b128 v[90:93], v35 offset:54528
	ds_read_b128 v[94:97], v35 offset:54544
	ds_read_b128 v[98:101], v35 offset:54560
	ds_read_b128 v[102:105], v35 offset:54576
	ds_read_b128 v[106:109], v35 offset:54592
	v_pk_fma_f32 v[38:39], v[228:229], v[4:5], v[38:39] neg_lo:[1,0,0] neg_hi:[1,0,0]
	v_pk_fma_f32 v[40:41], v[230:231], v[6:7], v[40:41] neg_lo:[1,0,0] neg_hi:[1,0,0]
	v_pk_fma_f32 v[38:39], v[232:233], v[8:9], v[38:39] neg_lo:[1,0,0] neg_hi:[1,0,0]
	v_pk_fma_f32 v[40:41], v[234:235], v[10:11], v[40:41] neg_lo:[1,0,0] neg_hi:[1,0,0]
	v_pk_fma_f32 v[38:39], v[236:237], v[12:13], v[38:39] neg_lo:[1,0,0] neg_hi:[1,0,0]
	v_pk_fma_f32 v[40:41], v[238:239], v[14:15], v[40:41] neg_lo:[1,0,0] neg_hi:[1,0,0]
	s_waitcnt lgkmcnt(5)
	v_fma_f32 v42, -v240, v0, v17
	v_add_f32_e32 v38, v39, v38
	v_fma_f32 v43, -v241, v1, 0
	v_add_f32_e32 v40, v40, v41
	v_pk_fma_f32 v[44:45], v[242:243], v[2:3], v[46:47] neg_lo:[1,0,0] neg_hi:[1,0,0]
	v_add_f32_e32 v16, v38, v40
	ds_read_b128 v[110:113], v35 offset:54784
	ds_read_b128 v[114:117], v35 offset:54800
	ds_read_b128 v[118:121], v35 offset:54816
	ds_read_b128 v[122:125], v35 offset:54832
	ds_read_b128 v[212:215], v35 offset:54848
	v_pk_fma_f32 v[42:43], v[62:63], v[4:5], v[42:43] neg_lo:[1,0,0] neg_hi:[1,0,0]
	v_pk_fma_f32 v[44:45], v[64:65], v[6:7], v[44:45] neg_lo:[1,0,0] neg_hi:[1,0,0]
	v_pk_fma_f32 v[42:43], v[78:79], v[8:9], v[42:43] neg_lo:[1,0,0] neg_hi:[1,0,0]
	v_pk_fma_f32 v[44:45], v[80:81], v[10:11], v[44:45] neg_lo:[1,0,0] neg_hi:[1,0,0]
	v_pk_fma_f32 v[42:43], v[82:83], v[12:13], v[42:43] neg_lo:[1,0,0] neg_hi:[1,0,0]
	v_pk_fma_f32 v[44:45], v[84:85], v[14:15], v[44:45] neg_lo:[1,0,0] neg_hi:[1,0,0]
	v_pk_fma_f32 v[42:43], v[86:87], v[16:17], v[42:43] neg_lo:[1,0,0] neg_hi:[1,0,0]
	s_waitcnt lgkmcnt(5)
	v_fma_f32 v38, -v90, v0, v18
	v_add_f32_e32 v42, v43, v42
	v_fma_f32 v39, -v91, v1, 0
	v_add_f32_e32 v44, v44, v45
	v_pk_fma_f32 v[40:41], v[92:93], v[2:3], v[46:47] neg_lo:[1,0,0] neg_hi:[1,0,0]
	v_add_f32_e32 v17, v42, v44
	ds_read_b128 v[216:219], v35 offset:55040
	ds_read_b128 v[220:223], v35 offset:55056
	ds_read_b128 v[224:227], v35 offset:55072
	ds_read_b128 v[228:231], v35 offset:55088
	ds_read_b128 v[232:235], v35 offset:55104
	v_pk_fma_f32 v[38:39], v[94:95], v[4:5], v[38:39] neg_lo:[1,0,0] neg_hi:[1,0,0]
	v_pk_fma_f32 v[40:41], v[96:97], v[6:7], v[40:41] neg_lo:[1,0,0] neg_hi:[1,0,0]
	v_pk_fma_f32 v[38:39], v[98:99], v[8:9], v[38:39] neg_lo:[1,0,0] neg_hi:[1,0,0]
	v_pk_fma_f32 v[40:41], v[100:101], v[10:11], v[40:41] neg_lo:[1,0,0] neg_hi:[1,0,0]
	v_pk_fma_f32 v[38:39], v[102:103], v[12:13], v[38:39] neg_lo:[1,0,0] neg_hi:[1,0,0]
	v_pk_fma_f32 v[40:41], v[104:105], v[14:15], v[40:41] neg_lo:[1,0,0] neg_hi:[1,0,0]
	v_pk_fma_f32 v[38:39], v[106:107], v[16:17], v[38:39] neg_lo:[1,0,0] neg_hi:[1,0,0]
	s_waitcnt lgkmcnt(5)
; DI void dn_prep_item(const Params& p, int l, int item, int next_item, u32x4 (&pre)[12], unsigned char* lds, int tid) {
;     ...
;             f32x4 cur[8], nxt[8];
;             cur[0] = *(const f32x4*)(Lb + 64);
; #pragma unroll
;             for (int i = 1; i < 32; ++i) {
;                 if (i < 31) {
; #pragma unroll
;                     for (int q = 0; q < 8; ++q) if (4 * q < i + 1) nxt[q] = *(const f32x4*)(Lb + (i + 1) * 64 + 4 * q);
;                 }
;                 float a0 = x[i], a1 = 0.f, a2 = 0.f, a3 = 0.f;
; #pragma unroll
;                 for (int j = 0; j < i; ++j) { const float lv = cur[j >> 2][j & 3];
;                     if ((j & 3) == 0) a0 -= lv * x[j]; else if ((j & 3) == 1) a1 -= lv * x[j]; else if ((j & 3) == 2) a2 -= lv * x[j]; else a3 -= lv * x[j]; }
;                 x[i] = (a0 + a1) + (a2 + a3);
; #pragma unroll
;                 for (int q = 0; q < 8; ++q) cur[q] = nxt[q];
;             }
	v_fma_f32 v42, -v110, v0, v19
	v_add_f32_e32 v38, v39, v38
	v_fma_f32 v43, -v111, v1, 0
	v_add_f32_e32 v40, v40, v41
	v_pk_fma_f32 v[44:45], v[112:113], v[2:3], v[46:47] neg_lo:[1,0,0] neg_hi:[1,0,0]
	v_add_f32_e32 v18, v38, v40
	ds_read_b128 v[236:239], v35 offset:55296
	ds_read_b128 v[240:243], v35 offset:55312
	ds_read_b128 v[62:65], v35 offset:55328
	ds_read_b128 v[78:81], v35 offset:55344
	ds_read_b128 v[82:85], v35 offset:55360
	ds_read_b128 v[86:89], v35 offset:55376
	v_pk_fma_f32 v[42:43], v[114:115], v[4:5], v[42:43] neg_lo:[1,0,0] neg_hi:[1,0,0]
	v_pk_fma_f32 v[44:45], v[116:117], v[6:7], v[44:45] neg_lo:[1,0,0] neg_hi:[1,0,0]
	v_pk_fma_f32 v[42:43], v[118:119], v[8:9], v[42:43] neg_lo:[1,0,0] neg_hi:[1,0,0]
	v_pk_fma_f32 v[44:45], v[120:121], v[10:11], v[44:45] neg_lo:[1,0,0] neg_hi:[1,0,0]
	v_pk_fma_f32 v[42:43], v[122:123], v[12:13], v[42:43] neg_lo:[1,0,0] neg_hi:[1,0,0]
	v_pk_fma_f32 v[44:45], v[124:125], v[14:15], v[44:45] neg_lo:[1,0,0] neg_hi:[1,0,0]
	v_pk_fma_f32 v[42:43], v[212:213], v[16:17], v[42:43] neg_lo:[1,0,0] neg_hi:[1,0,0]
	v_pk_fma_f32 v[44:45], v[214:215], v[18:19], v[44:45] neg_lo:[1,0,0] neg_hi:[1,0,0]
	s_waitcnt lgkmcnt(6)
	v_fma_f32 v38, -v216, v0, v20
	v_add_f32_e32 v42, v43, v42
	v_fma_f32 v39, -v217, v1, 0
	v_add_f32_e32 v44, v44, v45
	v_pk_fma_f32 v[40:41], v[218:219], v[2:3], v[46:47] neg_lo:[1,0,0] neg_hi:[1,0,0]
	v_add_f32_e32 v19, v42, v44
	ds_read_b128 v[90:93], v35 offset:55552
	ds_read_b128 v[94:97], v35 offset:55568
	ds_read_b128 v[98:101], v35 offset:55584
	ds_read_b128 v[102:105], v35 offset:55600
	ds_read_b128 v[106:109], v35 offset:55616
	ds_read_b128 v[110:113], v35 offset:55632
	v_pk_fma_f32 v[38:39], v[220:221], v[4:5], v[38:39] neg_lo:[1,0,0] neg_hi:[1,0,0]
	v_pk_fma_f32 v[40:41], v[222:223], v[6:7], v[40:41] neg_lo:[1,0,0] neg_hi:[1,0,0]
	v_pk_fma_f32 v[38:39], v[224:225], v[8:9], v[38:39] neg_lo:[1,0,0] neg_hi:[1,0,0]
	v_pk_fma_f32 v[40:41], v[226:227], v[10:11], v[40:41] neg_lo:[1,0,0] neg_hi:[1,0,0]
	v_pk_fma_f32 v[38:39], v[228:229], v[12:13], v[38:39] neg_lo:[1,0,0] neg_hi:[1,0,0]
	v_pk_fma_f32 v[40:41], v[230:231], v[14:15], v[40:41] neg_lo:[1,0,0] neg_hi:[1,0,0]
	v_pk_fma_f32 v[38:39], v[232:233], v[16:17], v[38:39] neg_lo:[1,0,0] neg_hi:[1,0,0]
	v_pk_fma_f32 v[40:41], v[234:235], v[18:19], v[40:41] neg_lo:[1,0,0] neg_hi:[1,0,0]
	s_waitcnt lgkmcnt(6)
	v_fma_f32 v42, -v236, v0, v21
	v_add_f32_e32 v38, v39, v38
	v_fma_f32 v43, -v237, v1, 0
	v_add_f32_e32 v40, v40, v41
	v_pk_fma_f32 v[44:45], v[238:239], v[2:3], v[46:47] neg_lo:[1,0,0] neg_hi:[1,0,0]
	v_add_f32_e32 v20, v38, v40
	ds_read_b128 v[114:117], v35 offset:55808
	ds_read_b128 v[118:121], v35 offset:55824
	ds_read_b128 v[122:125], v35 offset:55840
	ds_read_b128 v[212:215], v35 offset:55856
	ds_read_b128 v[216:219], v35 offset:55872
	ds_read_b128 v[220:223], v35 offset:55888
	v_pk_fma_f32 v[42:43], v[240:241], v[4:5], v[42:43] neg_lo:[1,0,0] neg_hi:[1,0,0]
	v_pk_fma_f32 v[44:45], v[242:243], v[6:7], v[44:45] neg_lo:[1,0,0] neg_hi:[1,0,0]
	v_pk_fma_f32 v[42:43], v[62:63], v[8:9], v[42:43] neg_lo:[1,0,0] neg_hi:[1,0,0]
	v_pk_fma_f32 v[44:45], v[64:65], v[10:11], v[44:45] neg_lo:[1,0,0] neg_hi:[1,0,0]
	v_pk_fma_f32 v[42:43], v[78:79], v[12:13], v[42:43] neg_lo:[1,0,0] neg_hi:[1,0,0]
	v_pk_fma_f32 v[44:45], v[80:81], v[14:15], v[44:45] neg_lo:[1,0,0] neg_hi:[1,0,0]
	v_pk_fma_f32 v[42:43], v[82:83], v[16:17], v[42:43] neg_lo:[1,0,0] neg_hi:[1,0,0]
	v_pk_fma_f32 v[44:45], v[84:85], v[18:19], v[44:45] neg_lo:[1,0,0] neg_hi:[1,0,0]
	v_pk_fma_f32 v[42:43], v[86:87], v[20:21], v[42:43] neg_lo:[1,0,0] neg_hi:[1,0,0]
	s_waitcnt lgkmcnt(6)
	v_fma_f32 v38, -v90, v0, v22
	v_add_f32_e32 v42, v43, v42
	v_fma_f32 v39, -v91, v1, 0
	v_add_f32_e32 v44, v44, v45
	v_pk_fma_f32 v[40:41], v[92:93], v[2:3], v[46:47] neg_lo:[1,0,0] neg_hi:[1,0,0]
	v_add_f32_e32 v21, v42, v44
	ds_read_b128 v[224:227], v35 offset:56064
	ds_read_b128 v[228:231], v35 offset:56080
	ds_read_b128 v[232:235], v35 offset:56096
	ds_read_b128 v[236:239], v35 offset:56112
	ds_read_b128 v[240:243], v35 offset:56128
	ds_read_b128 v[62:65], v35 offset:56144
	v_pk_fma_f32 v[38:39], v[94:95], v[4:5], v[38:39] neg_lo:[1,0,0] neg_hi:[1,0,0]
	v_pk_fma_f32 v[40:41], v[96:97], v[6:7], v[40:41] neg_lo:[1,0,0] neg_hi:[1,0,0]
	v_pk_fma_f32 v[38:39], v[98:99], v[8:9], v[38:39] neg_lo:[1,0,0] neg_hi:[1,0,0]
	v_pk_fma_f32 v[40:41], v[100:101], v[10:11], v[40:41] neg_lo:[1,0,0] neg_hi:[1,0,0]
	v_pk_fma_f32 v[38:39], v[102:103], v[12:13], v[38:39] neg_lo:[1,0,0] neg_hi:[1,0,0]
	v_pk_fma_f32 v[40:41], v[104:105], v[14:15], v[40:41] neg_lo:[1,0,0] neg_hi:[1,0,0]
	v_pk_fma_f32 v[38:39], v[106:107], v[16:17], v[38:39] neg_lo:[1,0,0] neg_hi:[1,0,0]
	v_pk_fma_f32 v[40:41], v[108:109], v[18:19], v[40:41] neg_lo:[1,0,0] neg_hi:[1,0,0]
	v_pk_fma_f32 v[38:39], v[110:111], v[20:21], v[38:39] neg_lo:[1,0,0] neg_hi:[1,0,0]
	s_waitcnt lgkmcnt(6)
	v_fma_f32 v42, -v114, v0, v23
	v_add_f32_e32 v38, v39, v38
	v_fma_f32 v43, -v115, v1, 0
	v_add_f32_e32 v40, v40, v41
	v_pk_fma_f32 v[44:45], v[116:117], v[2:3], v[46:47] neg_lo:[1,0,0] neg_hi:[1,0,0]
	v_add_f32_e32 v22, v38, v40
	v_pk_fma_f32 v[42:43], v[118:119], v[4:5], v[42:43] neg_lo:[1,0,0] neg_hi:[1,0,0]
	v_pk_fma_f32 v[44:45], v[120:121], v[6:7], v[44:45] neg_lo:[1,0,0] neg_hi:[1,0,0]
	v_pk_fma_f32 v[42:43], v[122:123], v[8:9], v[42:43] neg_lo:[1,0,0] neg_hi:[1,0,0]
	v_pk_fma_f32 v[44:45], v[124:125], v[10:11], v[44:45] neg_lo:[1,0,0] neg_hi:[1,0,0]
	v_pk_fma_f32 v[42:43], v[212:213], v[12:13], v[42:43] neg_lo:[1,0,0] neg_hi:[1,0,0]
	v_pk_fma_f32 v[44:45], v[214:215], v[14:15], v[44:45] neg_lo:[1,0,0] neg_hi:[1,0,0]
	v_pk_fma_f32 v[42:43], v[216:217], v[16:17], v[42:43] neg_lo:[1,0,0] neg_hi:[1,0,0]
	v_pk_fma_f32 v[44:45], v[218:219], v[18:19], v[44:45] neg_lo:[1,0,0] neg_hi:[1,0,0]
	v_pk_fma_f32 v[42:43], v[220:221], v[20:21], v[42:43] neg_lo:[1,0,0] neg_hi:[1,0,0]
	v_pk_fma_f32 v[44:45], v[222:223], v[22:23], v[44:45] neg_lo:[1,0,0] neg_hi:[1,0,0]
	s_waitcnt lgkmcnt(0)
; DI void dn_prep_item(const Params& p, int l, int item, int next_item, u32x4 (&pre)[12], unsigned char* lds, int tid) {
;     ...
;             f32x4 cur[8], nxt[8];
;             cur[0] = *(const f32x4*)(Lb + 64);
; #pragma unroll
;             for (int i = 1; i < 32; ++i) {
;                 if (i < 31) {
; #pragma unroll
;                     for (int q = 0; q < 8; ++q) if (4 * q < i + 1) nxt[q] = *(const f32x4*)(Lb + (i + 1) * 64 + 4 * q);
;                 }
;                 float a0 = x[i], a1 = 0.f, a2 = 0.f, a3 = 0.f;
; #pragma unroll
;                 for (int j = 0; j < i; ++j) { const float lv = cur[j >> 2][j & 3];
;                     if ((j & 3) == 0) a0 -= lv * x[j]; else if ((j & 3) == 1) a1 -= lv * x[j]; else if ((j & 3) == 2) a2 -= lv * x[j]; else a3 -= lv * x[j]; }
;                 x[i] = (a0 + a1) + (a2 + a3);
; #pragma unroll
;                 for (int q = 0; q < 8; ++q) cur[q] = nxt[q];
;             }
	v_fma_f32 v38, -v224, v0, v24
	v_add_f32_e32 v42, v43, v42
	v_fma_f32 v39, -v225, v1, 0
	v_add_f32_e32 v44, v44, v45
	v_pk_fma_f32 v[40:41], v[226:227], v[2:3], v[46:47] neg_lo:[1,0,0] neg_hi:[1,0,0]
	v_add_f32_e32 v23, v42, v44
	ds_read_b128 v[78:81], v35 offset:56320
	ds_read_b128 v[82:85], v35 offset:56336
	ds_read_b128 v[86:89], v35 offset:56352
	ds_read_b128 v[90:93], v35 offset:56368
	ds_read_b128 v[94:97], v35 offset:56384
	ds_read_b128 v[98:101], v35 offset:56400
	ds_read_b128 v[102:105], v35 offset:56416
	v_pk_fma_f32 v[38:39], v[228:229], v[4:5], v[38:39] neg_lo:[1,0,0] neg_hi:[1,0,0]
	v_pk_fma_f32 v[40:41], v[230:231], v[6:7], v[40:41] neg_lo:[1,0,0] neg_hi:[1,0,0]
	v_pk_fma_f32 v[38:39], v[232:233], v[8:9], v[38:39] neg_lo:[1,0,0] neg_hi:[1,0,0]
	v_pk_fma_f32 v[40:41], v[234:235], v[10:11], v[40:41] neg_lo:[1,0,0] neg_hi:[1,0,0]
	v_pk_fma_f32 v[38:39], v[236:237], v[12:13], v[38:39] neg_lo:[1,0,0] neg_hi:[1,0,0]
	v_pk_fma_f32 v[40:41], v[238:239], v[14:15], v[40:41] neg_lo:[1,0,0] neg_hi:[1,0,0]
	v_pk_fma_f32 v[38:39], v[240:241], v[16:17], v[38:39] neg_lo:[1,0,0] neg_hi:[1,0,0]
	v_pk_fma_f32 v[40:41], v[242:243], v[18:19], v[40:41] neg_lo:[1,0,0] neg_hi:[1,0,0]
	v_pk_fma_f32 v[38:39], v[62:63], v[20:21], v[38:39] neg_lo:[1,0,0] neg_hi:[1,0,0]
	v_pk_fma_f32 v[40:41], v[64:65], v[22:23], v[40:41] neg_lo:[1,0,0] neg_hi:[1,0,0]
	s_waitcnt lgkmcnt(0)
	v_fma_f32 v42, -v78, v0, v25
	v_add_f32_e32 v38, v39, v38
	v_fma_f32 v43, -v79, v1, 0
	v_add_f32_e32 v40, v40, v41
	v_pk_fma_f32 v[44:45], v[80:81], v[2:3], v[46:47] neg_lo:[1,0,0] neg_hi:[1,0,0]
	v_add_f32_e32 v24, v38, v40
	ds_read_b128 v[106:109], v35 offset:56576
	ds_read_b128 v[110:113], v35 offset:56592
	ds_read_b128 v[114:117], v35 offset:56608
	ds_read_b128 v[118:121], v35 offset:56624
	ds_read_b128 v[122:125], v35 offset:56640
	ds_read_b128 v[212:215], v35 offset:56656
	ds_read_b128 v[216:219], v35 offset:56672
	v_pk_fma_f32 v[42:43], v[82:83], v[4:5], v[42:43] neg_lo:[1,0,0] neg_hi:[1,0,0]
	v_pk_fma_f32 v[44:45], v[84:85], v[6:7], v[44:45] neg_lo:[1,0,0] neg_hi:[1,0,0]
	v_pk_fma_f32 v[42:43], v[86:87], v[8:9], v[42:43] neg_lo:[1,0,0] neg_hi:[1,0,0]
	v_pk_fma_f32 v[44:45], v[88:89], v[10:11], v[44:45] neg_lo:[1,0,0] neg_hi:[1,0,0]
	v_pk_fma_f32 v[42:43], v[90:91], v[12:13], v[42:43] neg_lo:[1,0,0] neg_hi:[1,0,0]
	v_pk_fma_f32 v[44:45], v[92:93], v[14:15], v[44:45] neg_lo:[1,0,0] neg_hi:[1,0,0]
	v_pk_fma_f32 v[42:43], v[94:95], v[16:17], v[42:43] neg_lo:[1,0,0] neg_hi:[1,0,0]
	v_pk_fma_f32 v[44:45], v[96:97], v[18:19], v[44:45] neg_lo:[1,0,0] neg_hi:[1,0,0]
	v_pk_fma_f32 v[42:43], v[98:99], v[20:21], v[42:43] neg_lo:[1,0,0] neg_hi:[1,0,0]
	v_pk_fma_f32 v[44:45], v[100:101], v[22:23], v[44:45] neg_lo:[1,0,0] neg_hi:[1,0,0]
	v_pk_fma_f32 v[42:43], v[102:103], v[24:25], v[42:43] neg_lo:[1,0,0] neg_hi:[1,0,0]
	s_waitcnt lgkmcnt(0)
	v_fma_f32 v38, -v106, v0, v26
	v_add_f32_e32 v42, v43, v42
	v_fma_f32 v39, -v107, v1, 0
	v_add_f32_e32 v44, v44, v45
	v_pk_fma_f32 v[40:41], v[108:109], v[2:3], v[46:47] neg_lo:[1,0,0] neg_hi:[1,0,0]
	v_add_f32_e32 v25, v42, v44
	ds_read_b128 v[220:223], v35 offset:56832
	ds_read_b128 v[224:227], v35 offset:56848
	ds_read_b128 v[228:231], v35 offset:56864
	ds_read_b128 v[232:235], v35 offset:56880
	ds_read_b128 v[236:239], v35 offset:56896
	ds_read_b128 v[240:243], v35 offset:56912
	ds_read_b128 v[62:65], v35 offset:56928
	v_pk_fma_f32 v[38:39], v[110:111], v[4:5], v[38:39] neg_lo:[1,0,0] neg_hi:[1,0,0]
	v_pk_fma_f32 v[40:41], v[112:113], v[6:7], v[40:41] neg_lo:[1,0,0] neg_hi:[1,0,0]
	v_pk_fma_f32 v[38:39], v[114:115], v[8:9], v[38:39] neg_lo:[1,0,0] neg_hi:[1,0,0]
	v_pk_fma_f32 v[40:41], v[116:117], v[10:11], v[40:41] neg_lo:[1,0,0] neg_hi:[1,0,0]
	v_pk_fma_f32 v[38:39], v[118:119], v[12:13], v[38:39] neg_lo:[1,0,0] neg_hi:[1,0,0]
	v_pk_fma_f32 v[40:41], v[120:121], v[14:15], v[40:41] neg_lo:[1,0,0] neg_hi:[1,0,0]
	v_pk_fma_f32 v[38:39], v[122:123], v[16:17], v[38:39] neg_lo:[1,0,0] neg_hi:[1,0,0]
	v_pk_fma_f32 v[40:41], v[124:125], v[18:19], v[40:41] neg_lo:[1,0,0] neg_hi:[1,0,0]
	v_pk_fma_f32 v[38:39], v[212:213], v[20:21], v[38:39] neg_lo:[1,0,0] neg_hi:[1,0,0]
	v_pk_fma_f32 v[40:41], v[214:215], v[22:23], v[40:41] neg_lo:[1,0,0] neg_hi:[1,0,0]
	v_pk_fma_f32 v[38:39], v[216:217], v[24:25], v[38:39] neg_lo:[1,0,0] neg_hi:[1,0,0]
	s_waitcnt lgkmcnt(0)
	v_fma_f32 v42, -v220, v0, v27
	v_add_f32_e32 v38, v39, v38
	v_fma_f32 v43, -v221, v1, 0
	v_add_f32_e32 v40, v40, v41
	v_pk_fma_f32 v[44:45], v[222:223], v[2:3], v[46:47] neg_lo:[1,0,0] neg_hi:[1,0,0]
	v_add_f32_e32 v26, v38, v40
	ds_read_b128 v[78:81], v35 offset:57088
	ds_read_b128 v[82:85], v35 offset:57104
	ds_read_b128 v[86:89], v35 offset:57120
	ds_read_b128 v[90:93], v35 offset:57136
	ds_read_b128 v[94:97], v35 offset:57152
	ds_read_b128 v[98:101], v35 offset:57168
	ds_read_b128 v[102:105], v35 offset:57184
	v_pk_fma_f32 v[42:43], v[224:225], v[4:5], v[42:43] neg_lo:[1,0,0] neg_hi:[1,0,0]
	v_pk_fma_f32 v[44:45], v[226:227], v[6:7], v[44:45] neg_lo:[1,0,0] neg_hi:[1,0,0]
	v_pk_fma_f32 v[42:43], v[228:229], v[8:9], v[42:43] neg_lo:[1,0,0] neg_hi:[1,0,0]
	v_pk_fma_f32 v[44:45], v[230:231], v[10:11], v[44:45] neg_lo:[1,0,0] neg_hi:[1,0,0]
	v_pk_fma_f32 v[42:43], v[232:233], v[12:13], v[42:43] neg_lo:[1,0,0] neg_hi:[1,0,0]
	v_pk_fma_f32 v[44:45], v[234:235], v[14:15], v[44:45] neg_lo:[1,0,0] neg_hi:[1,0,0]
	v_pk_fma_f32 v[42:43], v[236:237], v[16:17], v[42:43] neg_lo:[1,0,0] neg_hi:[1,0,0]
	v_pk_fma_f32 v[44:45], v[238:239], v[18:19], v[44:45] neg_lo:[1,0,0] neg_hi:[1,0,0]
	v_pk_fma_f32 v[42:43], v[240:241], v[20:21], v[42:43] neg_lo:[1,0,0] neg_hi:[1,0,0]
	v_pk_fma_f32 v[44:45], v[242:243], v[22:23], v[44:45] neg_lo:[1,0,0] neg_hi:[1,0,0]
	v_pk_fma_f32 v[42:43], v[62:63], v[24:25], v[42:43] neg_lo:[1,0,0] neg_hi:[1,0,0]
	v_pk_fma_f32 v[44:45], v[64:65], v[26:27], v[44:45] neg_lo:[1,0,0] neg_hi:[1,0,0]
	s_waitcnt lgkmcnt(0)
; DI void dn_prep_item(const Params& p, int l, int item, int next_item, u32x4 (&pre)[12], unsigned char* lds, int tid) {
;     ...
;             f32x4 cur[8], nxt[8];
;             cur[0] = *(const f32x4*)(Lb + 64);
; #pragma unroll
;             for (int i = 1; i < 32; ++i) {
;                 if (i < 31) {
; #pragma unroll
;                     for (int q = 0; q < 8; ++q) if (4 * q < i + 1) nxt[q] = *(const f32x4*)(Lb + (i + 1) * 64 + 4 * q);
;                 }
;                 float a0 = x[i], a1 = 0.f, a2 = 0.f, a3 = 0.f;
; #pragma unroll
;                 for (int j = 0; j < i; ++j) { const float lv = cur[j >> 2][j & 3];
;                     if ((j & 3) == 0) a0 -= lv * x[j]; else if ((j & 3) == 1) a1 -= lv * x[j]; else if ((j & 3) == 2) a2 -= lv * x[j]; else a3 -= lv * x[j]; }
;                 x[i] = (a0 + a1) + (a2 + a3);
; #pragma unroll
;                 for (int q = 0; q < 8; ++q) cur[q] = nxt[q];
;             }
	v_fma_f32 v38, -v78, v0, v36
	v_add_f32_e32 v42, v43, v42
	v_fma_f32 v39, -v79, v1, 0
	v_add_f32_e32 v44, v44, v45
	v_pk_fma_f32 v[40:41], v[80:81], v[2:3], v[46:47] neg_lo:[1,0,0] neg_hi:[1,0,0]
	v_add_f32_e32 v27, v42, v44
	ds_read_b128 v[106:109], v35 offset:57344
	ds_read_b128 v[110:113], v35 offset:57360
	ds_read_b128 v[114:117], v35 offset:57376
	ds_read_b128 v[118:121], v35 offset:57392
	ds_read_b128 v[122:125], v35 offset:57408
	ds_read_b128 v[212:215], v35 offset:57424
	ds_read_b128 v[216:219], v35 offset:57440
	ds_read_b128 v[220:223], v35 offset:57456
	v_pk_fma_f32 v[38:39], v[82:83], v[4:5], v[38:39] neg_lo:[1,0,0] neg_hi:[1,0,0]
	v_pk_fma_f32 v[40:41], v[84:85], v[6:7], v[40:41] neg_lo:[1,0,0] neg_hi:[1,0,0]
	v_pk_fma_f32 v[38:39], v[86:87], v[8:9], v[38:39] neg_lo:[1,0,0] neg_hi:[1,0,0]
	v_pk_fma_f32 v[40:41], v[88:89], v[10:11], v[40:41] neg_lo:[1,0,0] neg_hi:[1,0,0]
	v_pk_fma_f32 v[38:39], v[90:91], v[12:13], v[38:39] neg_lo:[1,0,0] neg_hi:[1,0,0]
	v_pk_fma_f32 v[40:41], v[92:93], v[14:15], v[40:41] neg_lo:[1,0,0] neg_hi:[1,0,0]
	v_pk_fma_f32 v[38:39], v[94:95], v[16:17], v[38:39] neg_lo:[1,0,0] neg_hi:[1,0,0]
	v_pk_fma_f32 v[40:41], v[96:97], v[18:19], v[40:41] neg_lo:[1,0,0] neg_hi:[1,0,0]
	v_pk_fma_f32 v[38:39], v[98:99], v[20:21], v[38:39] neg_lo:[1,0,0] neg_hi:[1,0,0]
	v_pk_fma_f32 v[40:41], v[100:101], v[22:23], v[40:41] neg_lo:[1,0,0] neg_hi:[1,0,0]
	v_pk_fma_f32 v[38:39], v[102:103], v[24:25], v[38:39] neg_lo:[1,0,0] neg_hi:[1,0,0]
	v_pk_fma_f32 v[40:41], v[104:105], v[26:27], v[40:41] neg_lo:[1,0,0] neg_hi:[1,0,0]
	s_waitcnt lgkmcnt(0)
	v_fma_f32 v42, -v106, v0, v28
	v_add_f32_e32 v38, v39, v38
	v_fma_f32 v43, -v107, v1, 0
	v_add_f32_e32 v40, v40, v41
	v_pk_fma_f32 v[44:45], v[108:109], v[2:3], v[46:47] neg_lo:[1,0,0] neg_hi:[1,0,0]
	v_add_f32_e32 v36, v38, v40
	ds_read_b128 v[224:227], v35 offset:57600
	ds_read_b128 v[228:231], v35 offset:57616
	ds_read_b128 v[232:235], v35 offset:57632
	ds_read_b128 v[236:239], v35 offset:57648
	ds_read_b128 v[240:243], v35 offset:57664
	ds_read_b128 v[62:65], v35 offset:57680
	ds_read_b128 v[78:81], v35 offset:57696
	ds_read_b128 v[82:85], v35 offset:57712
	v_pk_fma_f32 v[42:43], v[110:111], v[4:5], v[42:43] neg_lo:[1,0,0] neg_hi:[1,0,0]
	v_pk_fma_f32 v[44:45], v[112:113], v[6:7], v[44:45] neg_lo:[1,0,0] neg_hi:[1,0,0]
	v_pk_fma_f32 v[42:43], v[114:115], v[8:9], v[42:43] neg_lo:[1,0,0] neg_hi:[1,0,0]
	v_pk_fma_f32 v[44:45], v[116:117], v[10:11], v[44:45] neg_lo:[1,0,0] neg_hi:[1,0,0]
	v_pk_fma_f32 v[42:43], v[118:119], v[12:13], v[42:43] neg_lo:[1,0,0] neg_hi:[1,0,0]
	v_pk_fma_f32 v[44:45], v[120:121], v[14:15], v[44:45] neg_lo:[1,0,0] neg_hi:[1,0,0]
	v_pk_fma_f32 v[42:43], v[122:123], v[16:17], v[42:43] neg_lo:[1,0,0] neg_hi:[1,0,0]
	v_pk_fma_f32 v[44:45], v[124:125], v[18:19], v[44:45] neg_lo:[1,0,0] neg_hi:[1,0,0]
	v_pk_fma_f32 v[42:43], v[212:213], v[20:21], v[42:43] neg_lo:[1,0,0] neg_hi:[1,0,0]
	v_pk_fma_f32 v[44:45], v[214:215], v[22:23], v[44:45] neg_lo:[1,0,0] neg_hi:[1,0,0]
	v_pk_fma_f32 v[42:43], v[216:217], v[24:25], v[42:43] neg_lo:[1,0,0] neg_hi:[1,0,0]
	v_pk_fma_f32 v[44:45], v[218:219], v[26:27], v[44:45] neg_lo:[1,0,0] neg_hi:[1,0,0]
	v_fma_f32 v42, -v220, v36, v42
	s_waitcnt lgkmcnt(0)
	v_fma_f32 v38, -v224, v0, v29
	v_add_f32_e32 v42, v43, v42
	v_fma_f32 v39, -v225, v1, 0
	v_add_f32_e32 v44, v44, v45
	v_pk_fma_f32 v[40:41], v[226:227], v[2:3], v[46:47] neg_lo:[1,0,0] neg_hi:[1,0,0]
	v_add_f32_e32 v28, v42, v44
	ds_read_b128 v[86:89], v35 offset:57856
	ds_read_b128 v[90:93], v35 offset:57872
	ds_read_b128 v[94:97], v35 offset:57888
	ds_read_b128 v[98:101], v35 offset:57904
	ds_read_b128 v[102:105], v35 offset:57920
	ds_read_b128 v[106:109], v35 offset:57936
	ds_read_b128 v[110:113], v35 offset:57952
	ds_read_b128 v[114:117], v35 offset:57968
	v_pk_fma_f32 v[38:39], v[228:229], v[4:5], v[38:39] neg_lo:[1,0,0] neg_hi:[1,0,0]
	v_pk_fma_f32 v[40:41], v[230:231], v[6:7], v[40:41] neg_lo:[1,0,0] neg_hi:[1,0,0]
	v_pk_fma_f32 v[38:39], v[232:233], v[8:9], v[38:39] neg_lo:[1,0,0] neg_hi:[1,0,0]
	v_pk_fma_f32 v[40:41], v[234:235], v[10:11], v[40:41] neg_lo:[1,0,0] neg_hi:[1,0,0]
	v_pk_fma_f32 v[38:39], v[236:237], v[12:13], v[38:39] neg_lo:[1,0,0] neg_hi:[1,0,0]
	v_pk_fma_f32 v[40:41], v[238:239], v[14:15], v[40:41] neg_lo:[1,0,0] neg_hi:[1,0,0]
	v_pk_fma_f32 v[38:39], v[240:241], v[16:17], v[38:39] neg_lo:[1,0,0] neg_hi:[1,0,0]
	v_pk_fma_f32 v[40:41], v[242:243], v[18:19], v[40:41] neg_lo:[1,0,0] neg_hi:[1,0,0]
	v_pk_fma_f32 v[38:39], v[62:63], v[20:21], v[38:39] neg_lo:[1,0,0] neg_hi:[1,0,0]
	v_pk_fma_f32 v[40:41], v[64:65], v[22:23], v[40:41] neg_lo:[1,0,0] neg_hi:[1,0,0]
	v_pk_fma_f32 v[38:39], v[78:79], v[24:25], v[38:39] neg_lo:[1,0,0] neg_hi:[1,0,0]
	v_pk_fma_f32 v[40:41], v[80:81], v[26:27], v[40:41] neg_lo:[1,0,0] neg_hi:[1,0,0]
	v_fma_f32 v38, -v82, v36, v38
	v_fma_f32 v39, -v83, v28, v39
	s_waitcnt lgkmcnt(0)
	v_fma_f32 v42, -v86, v0, v37
	v_add_f32_e32 v38, v39, v38
	v_fma_f32 v43, -v87, v1, 0
	v_add_f32_e32 v40, v40, v41
	v_pk_fma_f32 v[44:45], v[88:89], v[2:3], v[46:47] neg_lo:[1,0,0] neg_hi:[1,0,0]
	v_add_f32_e32 v29, v38, v40
	v_pk_fma_f32 v[42:43], v[90:91], v[4:5], v[42:43] neg_lo:[1,0,0] neg_hi:[1,0,0]
	v_pk_fma_f32 v[44:45], v[92:93], v[6:7], v[44:45] neg_lo:[1,0,0] neg_hi:[1,0,0]
	v_pk_fma_f32 v[42:43], v[94:95], v[8:9], v[42:43] neg_lo:[1,0,0] neg_hi:[1,0,0]
	v_pk_fma_f32 v[44:45], v[96:97], v[10:11], v[44:45] neg_lo:[1,0,0] neg_hi:[1,0,0]
	v_pk_fma_f32 v[42:43], v[98:99], v[12:13], v[42:43] neg_lo:[1,0,0] neg_hi:[1,0,0]
	v_pk_fma_f32 v[44:45], v[100:101], v[14:15], v[44:45] neg_lo:[1,0,0] neg_hi:[1,0,0]
	v_pk_fma_f32 v[42:43], v[102:103], v[16:17], v[42:43] neg_lo:[1,0,0] neg_hi:[1,0,0]
	v_pk_fma_f32 v[44:45], v[104:105], v[18:19], v[44:45] neg_lo:[1,0,0] neg_hi:[1,0,0]
	v_pk_fma_f32 v[42:43], v[106:107], v[20:21], v[42:43] neg_lo:[1,0,0] neg_hi:[1,0,0]
	v_pk_fma_f32 v[44:45], v[108:109], v[22:23], v[44:45] neg_lo:[1,0,0] neg_hi:[1,0,0]
	v_pk_fma_f32 v[42:43], v[110:111], v[24:25], v[42:43] neg_lo:[1,0,0] neg_hi:[1,0,0]
	v_pk_fma_f32 v[44:45], v[112:113], v[26:27], v[44:45] neg_lo:[1,0,0] neg_hi:[1,0,0]
	v_fma_f32 v42, -v114, v36, v42
	v_fma_f32 v43, -v115, v28, v43
	v_fma_f32 v44, -v116, v29, v44
	v_add_f32_e32 v42, v43, v42
	v_add_f32_e32 v44, v44, v45
	v_add_f32_e32 v35, v42, v44
	s_and_saveexec_b64 s[6:7], vcc
	s_xor_b64 s[6:7], exec, s[6:7]
	s_cbranch_execz .LBB0_498
; DI void dn_prep_item(const Params& p, int l, int item, int next_item, u32x4 (&pre)[12], unsigned char* lds, int tid) {
;     ...
;             if (wv < 4) {
; #pragma unroll
;                 for (int i = 0; i < 32; ++i) XS[(r0 + i) * 129 + c] = x[i];
;             } else if (lane < 32) {
; #pragma unroll
;                 for (int i = 0; i < 32; ++i) Zs[i * 33 + c] = x[i];
;             }
	v_mul_u32_u24_e32 v30, 0x204, v33
	v_lshlrev_b32_e32 v31, 2, v32
	v_add3_u32 v30, v50, v30, v31
	ds_write2_b32 v30, v0, v1 offset1:129
	v_add_u32_e32 v0, 0x400, v30
	ds_write2_b32 v0, v2, v3 offset0:2 offset1:131
	v_add_u32_e32 v0, 0x800, v30
	ds_write2_b32 v0, v4, v5 offset0:4 offset1:133
	v_add_u32_e32 v0, 0xc00, v30
	ds_write2_b32 v0, v6, v7 offset0:6 offset1:135
	v_add_u32_e32 v0, 0x1000, v30
	ds_write2_b32 v0, v8, v9 offset0:8 offset1:137
	v_add_u32_e32 v0, 0x1400, v30
	ds_write2_b32 v0, v10, v11 offset0:10 offset1:139
	v_add_u32_e32 v0, 0x1800, v30
	ds_write2_b32 v0, v12, v13 offset0:12 offset1:141
	v_add_u32_e32 v0, 0x1c00, v30
	ds_write2_b32 v0, v14, v15 offset0:14 offset1:143
	v_add_u32_e32 v0, 0x2000, v30
	ds_write2_b32 v0, v16, v17 offset0:16 offset1:145
	v_add_u32_e32 v0, 0x2400, v30
	ds_write2_b32 v0, v18, v19 offset0:18 offset1:147
	v_add_u32_e32 v0, 0x2800, v30
	ds_write2_b32 v0, v20, v21 offset0:20 offset1:149
	v_add_u32_e32 v0, 0x2c00, v30
	ds_write2_b32 v0, v22, v23 offset0:22 offset1:151
	v_add_u32_e32 v0, 0x3000, v30
	ds_write2_b32 v0, v24, v25 offset0:24 offset1:153
	v_add_u32_e32 v0, 0x3400, v30
	ds_write2_b32 v0, v26, v27 offset0:26 offset1:155
	v_add_u32_e32 v0, 0x3800, v30
	ds_write2_b32 v0, v36, v28 offset0:28 offset1:157
	v_add_u32_e32 v0, 0x3c00, v30
	ds_write2_b32 v0, v29, v35 offset0:30 offset1:159
